# attnB: K tile XOR swizzle over 16 chunks (row&15): ds_read_b128 of K conflict-free
# speedup vs baseline: 1.0113x; 1.0047x over previous
; #define DMA_K(t, slot) do { _Pragma("unroll") for (int i_ = 0; i_ < 2; ++i_) __builtin_amdgcn_global_load_lds((const unsigned*)(ksrc[i_] + (size_t)(t) * 64 * DM), (LAS unsigned*)(lds3 + (slot) + (i_ * 8 + wid) * 1024), 16, 0, 0); } while (0)
; #define DMA_V(t, slot) do { _Pragma("unroll") for (int i_ = 0; i_ < 2; ++i_) __builtin_amdgcn_global_load_lds((const unsigned*)(vsrc[i_] + (size_t)(t) * 64 * DM), (LAS unsigned*)(lds3 + RING + (slot) + (i_ * 8 + wid) * 1024), 16, 0, 0); } while (0)
; __device__ __forceinline__ void attnB_unit(const bf16* Q, const bf16* __restrict__ K, const bf16* __restrict__ V, bf16* O, long rowbase, int seq, int h, int q0, float lam, char* lds, LAS unsigned char* lds3) {
;     int tid_ = threadIdx.x; asm volatile("" : "+v"(tid_));
;     const int tid = tid_, wid = __builtin_amdgcn_readfirstlane(tid >> 6), lane = tid & 63, r32 = lane & 31, hi = lane >> 5, wq = wid & 3, c = wid >> 2;
;     constexpr int RING = 3 * SHM_KV;
;     char* K_lds = lds; char* V_lds = lds + RING;
;     float* ws = (float*)(lds + 2 * RING) + wid * 64; float* al_l = ws + 32;
;     float m_ref = 0.f, l_reg = 0.f; f32x16 o[4] = {}; f32x16 negm = {}; bf16x8 qr[4];
;     asm volatile("" : "+v"(negm));
;     const bf16* ksrc[2]; const bf16* vsrc[2];
; #pragma unroll
;     for (int i = 0; i < 2; ++i) { const int q = (i * 8 + wid) * 64 + lane;
;         { const int row = q >> 4, lc = (q & 15) ^ (row & 7); ksrc[i] = K + (size_t)(rowbase + row) * DM + h * 128 + lc * 8; }
;         { const int st = q >> 5, w = q & 31, k = (st >> 2) * 8 + (w >> 2), cc = (st & 3) * 32 + (w & 3) * 8;
;           vsrc[i] = V + (size_t)(rowbase + k) * DM + h * 128 + cc; } }
;     ...
;     DMA_K(0, 0); DMA_V(0, 0); DMA_K(1, SHM_KV);
;     const bf16* Qw = Q + (size_t)(rowbase + q0 + wq * 32 + r32) * DM + h * 128 + c * 64 + hi * 8;
; #pragma unroll
;     for (int d0 = 0; d0 < 4; ++d0) qr[d0] = *reinterpret_cast<const bf16x8*>(Qw + d0 * 16);
.LBB0_270:
	s_lshr_b32 s8, s4, 7
	s_sext_i32_i16 s0, s5
	v_cvt_f32_ubyte0_e32 v2, s8
	v_cvt_f32_i32_e32 v1, s0
	v_rcp_iflag_f32_e32 v3, v2
	s_ashr_i32 s0, s0, 30
	s_or_b32 s9, s0, 1
	v_mov_b32_e32 v38, v200
	v_mul_f32_e32 v3, v1, v3
	v_trunc_f32_e32 v3, v3
	v_fma_f32 v1, -v3, v2, v1
	v_cvt_i32_f32_e32 v3, v3
	v_cmp_ge_f32_e64 s[0:1], |v1|, v2
	s_and_b64 s[0:1], s[0:1], exec
	s_cselect_b32 s0, s9, 0
	v_readfirstlane_b32 s1, v3
	s_add_i32 s0, s1, s0
	s_sext_i32_i16 s1, s0
	s_mul_i32 s0, s0, s8
	s_sub_i32 s0, s5, s0
	s_sext_i32_i16 s0, s0
	s_lshl_b32 s5, s0, 7
	s_lshl_b32 s0, s1, 7
	v_readfirstlane_b32 s28, v38
	s_ashr_i32 s26, s28, 6
	s_ashr_i32 s1, s0, 31
	s_and_b32 s29, s26, 3
	s_and_b32 s27, s28, 0xffffffc0
	s_lshl_b64 s[0:1], s[0:1], 1
	v_lshlrev_b32_e32 v2, 3, v38
	s_add_u32 s8, s20, s0
	v_and_b32_e32 v114, 24, v2
	v_mov_b32_e32 v2, s28
	s_movk_i32 s47, 0xffc0
	s_addc_u32 s9, s21, s1
	v_bfi_b32 v115, s47, v2, v38
	v_and_b32_e32 v1, 15, v38
	s_add_u32 s18, s22, s0
	v_ashrrev_i32_e32 v2, 4, v115
	v_lshrrev_b32_e32 v8, 2, v38
	s_addc_u32 s19, s23, s1
	v_bitop3_b32 v4, v2, v1, 15 bitop3:0x6c
	s_ashr_i32 s47, s28, 4
	v_ashrrev_i32_e32 v3, 31, v2
	v_lshlrev_b32_e32 v52, 4, v4
	v_bfi_b32 v4, -8, s47, v8
	v_lshl_add_u64 v[2:3], s[2:3], 0, v[2:3]
	v_ashrrev_i32_e32 v5, 31, v4
	v_lshlrev_b64 v[50:51], 11, v[2:3]
	v_lshl_add_u64 v[4:5], s[2:3], 0, v[4:5]
	v_and_b32_e32 v188, 63, v38
	v_lshl_add_u64 v[2:3], s[8:9], 0, v[50:51]
	v_mov_b32_e32 v53, v0
	v_and_or_b32 v6, v115, s62, v114
	v_lshlrev_b64 v[54:55], 11, v[4:5]
	s_addk_i32 s27, 0x200
	v_lshl_add_u64 v[2:3], v[2:3], 0, v[52:53]
	v_lshl_add_u64 v[4:5], s[18:19], 0, v[54:55]
	v_lshlrev_b32_e32 v6, 1, v6
	v_mov_b32_e32 v7, v0
	v_or_b32_e32 v53, s27, v188
	v_lshl_add_u64 v[4:5], v[4:5], 0, v[6:7]
	v_ashrrev_i32_e32 v6, 4, v53
	v_ashrrev_i32_e32 v7, 31, v6
	v_bitop3_b32 v1, v6, v1, 15 bitop3:0x6c
	v_lshl_add_u64 v[6:7], s[2:3], 0, v[6:7]
	v_lshlrev_b64 v[56:57], 11, v[6:7]
	v_lshl_add_u64 v[6:7], s[8:9], 0, v[56:57]
	s_ashr_i32 s8, s27, 4
	v_bfi_b32 v8, -8, s8, v8
	s_lshl_b32 s8, s26, 10
	v_ashrrev_i32_e32 v9, 31, v8
	s_add_i32 s49, s8, 0
	v_mov_b32_e32 v18, v0
	v_mov_b32_e32 v19, v0
	v_mov_b32_e32 v20, v0
	v_mov_b32_e32 v21, v0
	v_mov_b32_e32 v22, v0
	v_mov_b32_e32 v23, v0
	v_mov_b32_e32 v24, v0
	v_mov_b32_e32 v25, v0
	v_mov_b32_e32 v26, v0
	v_mov_b32_e32 v27, v0
	v_mov_b32_e32 v28, v0
	v_mov_b32_e32 v29, v0
	v_mov_b32_e32 v30, v0
	v_mov_b32_e32 v31, v0
	v_mov_b32_e32 v32, v0
	v_mov_b32_e32 v33, v0
	v_lshlrev_b32_e32 v58, 4, v1
	v_mov_b32_e32 v59, v0
	v_lshl_add_u64 v[8:9], s[2:3], 0, v[8:9]
	s_mov_b32 m0, s49
	v_lshl_add_u64 v[6:7], v[6:7], 0, v[58:59]
	v_and_or_b32 v1, v53, s62, v114
	v_lshlrev_b64 v[60:61], 11, v[8:9]
	global_load_lds_dwordx4 v[2:3], off
	s_add_i32 m0, s49, 0x2000
	v_lshl_add_u64 v[8:9], s[18:19], 0, v[60:61]
	v_lshlrev_b32_e32 v10, 1, v1
	v_mov_b32_e32 v11, v0
	global_load_lds_dwordx4 v[6:7], off
	s_add_i32 m0, s49, 0xc000
	v_lshl_add_u64 v[8:9], v[8:9], 0, v[10:11]
	global_load_lds_dwordx4 v[4:5], off
	s_add_i32 m0, s49, 0xe000
	v_lshl_add_u64 v[10:11], v[2:3], 0, s[40:41]
	global_load_lds_dwordx4 v[8:9], off
	s_add_i32 m0, s49, 0x4000
	s_ashr_i32 s47, s28, 8
	global_load_lds_dwordx4 v[10:11], off
	s_add_i32 m0, s49, 0x6000
	s_ashr_i32 s8, s5, 31
	s_add_u32 s2, s2, s5
	s_addc_u32 s3, s3, s8
	s_lshl_b32 s5, s29, 5
	s_add_u32 s2, s5, s2
	v_and_b32_e32 v34, 31, v38
	v_lshl_add_u64 v[10:11], v[6:7], 0, s[40:41]
	v_mov_b32_e32 v35, v0
	s_addc_u32 s3, 0, s3
	global_load_lds_dwordx4 v[10:11], off
	v_lshl_add_u64 v[10:11], s[2:3], 0, v[34:35]
	v_lshlrev_b64 v[10:11], 11, v[10:11]
	v_lshl_add_u64 v[10:11], s[10:11], 0, v[10:11]
	s_lshl_b32 s2, s47, 6
	v_bfe_u32 v17, v38, 5, 1
	v_lshl_add_u64 v[166:167], v[10:11], 0, s[0:1]
	s_ashr_i32 s3, s2, 31
	v_lshl_add_u64 v[10:11], s[2:3], 1, v[166:167]
	v_lshlrev_b32_e32 v36, 4, v17
	v_mov_b32_e32 v37, v0
	v_lshl_add_u64 v[10:11], v[10:11], 0, v[36:37]
	global_load_dwordx4 v[158:161], v[10:11], off
	global_load_dwordx4 v[154:157], v[10:11], off offset:32
	global_load_dwordx4 v[150:153], v[10:11], off offset:64
	global_load_dwordx4 v[146:149], v[10:11], off offset:96
	s_waitcnt vmcnt(0) lgkmcnt(0)
	s_barrier
; __device__ __forceinline__ int v_rd_base(int lane) { return ((lane & 3) << 3) | (((lane >> 2) & 3) << 6) | (((lane >> 4) & 1) << 5) | (((lane >> 5) & 1) << 8); }
; #define WAIT_BAR(N) asm volatile("s_waitcnt vmcnt(" #N ") lgkmcnt(0)\n\ts_barrier" ::: "memory")
; #define DMA_K(t, slot) do { _Pragma("unroll") for (int i_ = 0; i_ < 2; ++i_) __builtin_amdgcn_global_load_lds((const unsigned*)(ksrc[i_] + (size_t)(t) * 64 * DM), (LAS unsigned*)(lds3 + (slot) + (i_ * 8 + wid) * 1024), 16, 0, 0); } while (0)
; #define DMA_V(t, slot) do { _Pragma("unroll") for (int i_ = 0; i_ < 2; ++i_) __builtin_amdgcn_global_load_lds((const unsigned*)(vsrc[i_] + (size_t)(t) * 64 * DM), (LAS unsigned*)(lds3 + RING + (slot) + (i_ * 8 + wid) * 1024), 16, 0, 0); } while (0)
; #define ROT() do { const int t_ = sl_prev; sl_prev = sl_cur; sl_cur = sl_next; sl_next = t_; } while (0)
; __device__ __forceinline__ void attnB_unit(const bf16* Q, const bf16* __restrict__ K, const bf16* __restrict__ V, bf16* O, long rowbase, int seq, int h, int q0, float lam, char* lds, LAS unsigned char* lds3) {
;     ...
;     const int vb0 = (int)(uintptr_t)V_lds + v_rd_base(lane);
;     ...
;     f32x16 pA0, pA1, pB0, pB1; float alA, alB; bf16x8 pa0, pa1, pa2, pa3; const int NT = seq / 64; const int colb0 = c * 128;
;     int sl_prev = 2 * SHM_KV, sl_cur = 0, sl_next = SHM_KV;
;     ...
;     WAIT_BAR(0);
;     DMA_K(2, sl_prev); DMA_V(1, sl_next);
;     qkt64n<256>(pA0, pA1, K_lds + sl_cur, qr, r32, hi, colb0, negm); partialSM2<true>(pA0, pA1, m_ref, alA, negm);
;     WAIT_BAR(4); ROT();
	s_add_i32 m0, s49, 0x8000
	v_lshl_add_u64 v[2:3], v[2:3], 0, s[86:87]
	s_lshr_b32 s50, s4, 6
	global_load_lds_dwordx4 v[2:3], off
	s_add_i32 m0, s49, 0xa000
	v_lshl_add_u64 v[2:3], v[6:7], 0, s[86:87]
	s_cmp_lg_u32 0, -1
	global_load_lds_dwordx4 v[2:3], off
	s_cselect_b32 s3, 0, 0
	s_add_i32 m0, s49, 0x10000
	v_lshl_add_u64 v[2:3], v[4:5], 0, s[40:41]
	global_load_lds_dwordx4 v[2:3], off
	v_lshl_add_u64 v[2:3], v[8:9], 0, s[40:41]
	s_add_i32 m0, s49, 0x12000
	v_lshlrev_b32_e32 v37, 4, v38
	global_load_lds_dwordx4 v[2:3], off
	v_lshlrev_b32_e32 v35, 3, v188
	v_and_b32_e32 v39, 0xc0, v37
	v_lshlrev_b32_e32 v38, 1, v38
	v_and_or_b32 v39, v35, 24, v39
	v_and_b32_e32 v38, 32, v38
	v_and_b32_e32 v35, 0x100, v35
	v_or3_b32 v35, v39, v38, v35
	s_add_i32 s3, s3, 0xc000
	v_add_u32_e32 v189, s3, v35
	s_lshl_b32 s3, s47, 7
	v_lshlrev_b32_e32 v191, 8, v34
	v_and_b32_e32 v59, 0xf0, v37
	v_add_u32_e32 v194, 0, v191
	v_or_b32_e32 v78, s3, v36
	v_bitop3_b32 v192, s3, v59, v36 bitop3:0x36
	v_add_u32_e32 v34, v194, v192
	v_bitop3_b32 v193, v78, v59, 32 bitop3:0x36
	ds_read_b128 v[62:65], v34
	ds_read_b128 v[66:69], v34 offset:8192
	v_add_u32_e32 v34, v194, v193
	ds_read_b128 v[70:73], v34
	ds_read_b128 v[74:77], v34 offset:8192
	s_waitcnt lgkmcnt(0)
	s_mov_b32 s2, 0
	s_mov_b32 s52, 4
	s_movk_i32 s51, 0x4000
	s_mov_b32 s48, 0x8000
	v_mov_b32_e32 v1, v0
	v_mov_b32_e32 v2, v0
	v_mov_b32_e32 v3, v0
	v_mov_b32_e32 v4, v0
	v_mov_b32_e32 v5, v0
	v_mov_b32_e32 v6, v0
	v_mov_b32_e32 v7, v0
	v_mov_b32_e32 v8, v0
	v_mov_b32_e32 v9, v0
	v_mov_b32_e32 v10, v0
	v_mov_b32_e32 v11, v0
	v_mov_b32_e32 v12, v0
	v_mov_b32_e32 v13, v0
	v_mov_b32_e32 v14, v0
	v_mov_b32_e32 v15, v0
	s_waitcnt vmcnt(0) lgkmcnt(0)
	v_mfma_f32_32x32x16_bf16 v[34:49], v[62:65], v[158:161], v[18:33]
	v_bitop3_b32 v190, v78, v59, 64 bitop3:0x36
	v_bitop3_b32 v195, v78, v59, s62 bitop3:0x36
	v_add_u32_e32 v59, v194, v195
	v_mfma_f32_32x32x16_bf16 v[18:33], v[66:69], v[158:161], v[18:33]
	v_add_u32_e32 v66, v194, v190
	ds_read_b128 v[62:65], v66
	ds_read_b128 v[66:69], v66 offset:8192
	v_mfma_f32_32x32x16_bf16 v[34:49], v[70:73], v[154:157], v[34:49]
	ds_read_b128 v[70:73], v59
	ds_read_b128 v[78:81], v59 offset:8192
	s_waitcnt lgkmcnt(0)
	v_mfma_f32_32x32x16_bf16 v[18:33], v[74:77], v[154:157], v[18:33]
	s_waitcnt lgkmcnt(3)
	v_mfma_f32_32x32x16_bf16 v[34:49], v[62:65], v[150:153], v[34:49]
	v_or_b32_e32 v56, v56, v58
	v_or_b32_e32 v50, v50, v52
	v_lshl_add_u64 v[172:173], s[14:15], 0, v[56:57]
	v_lshl_add_u64 v[174:175], s[14:15], 0, v[50:51]
	v_mov_b32_e32 v196, 0
	s_waitcnt lgkmcnt(1)
	v_mfma_f32_32x32x16_bf16 v[34:49], v[70:73], v[146:149], v[34:49]
	v_mfma_f32_32x32x16_bf16 v[18:33], v[66:69], v[150:153], v[18:33]
	s_nop 10
	v_max_f32_e32 v59, v35, v35
	v_max_f32_e32 v62, v34, v34
	v_max_f32_e32 v59, v62, v59
	v_max3_f32 v59, v59, v36, v37
	v_max3_f32 v59, v59, v38, v39
	v_max3_f32 v59, v59, v40, v41
	v_max3_f32 v59, v59, v42, v43
	s_waitcnt lgkmcnt(0)
	v_mfma_f32_32x32x16_bf16 v[18:33], v[78:81], v[146:149], v[18:33]
	v_max3_f32 v59, v59, v44, v45
	v_max3_f32 v59, v59, v46, v47
	v_max3_f32 v59, v59, v48, v49
	v_mov_b64_e32 v[80:81], v[14:15]
	v_mov_b64_e32 v[78:79], v[12:13]
	v_mov_b64_e32 v[76:77], v[10:11]
	v_mov_b64_e32 v[74:75], v[8:9]
	s_nop 4
	v_max3_f32 v59, v59, v18, v19
	v_max3_f32 v59, v59, v20, v21
	v_max3_f32 v59, v59, v22, v23
	v_max3_f32 v59, v59, v24, v25
	v_max3_f32 v59, v59, v26, v27
	v_max3_f32 v59, v59, v28, v29
	v_max3_f32 v59, v59, v30, v31
	v_max3_f32 v59, v59, v32, v33
	v_mov_b32_e32 v62, v59
	s_nop 1
	v_permlane32_swap_b32_e32 v59, v62
	v_max_f32_e32 v62, v62, v62
	v_max_f32_e32 v59, v59, v59
	v_max_f32_e32 v59, v59, v62
	v_sub_f32_e32 v98, v18, v59
	v_sub_f32_e32 v18, v34, v59
	v_exp_f32_e32 v212, v18
	v_sub_f32_e32 v18, v35, v59
	v_exp_f32_e32 v216, v18
	v_sub_f32_e32 v18, v36, v59
	v_exp_f32_e32 v213, v18
	v_sub_f32_e32 v18, v37, v59
	v_exp_f32_e32 v217, v18
	v_sub_f32_e32 v18, v38, v59
	v_exp_f32_e32 v214, v18
	v_sub_f32_e32 v18, v39, v59
	v_exp_f32_e32 v218, v18
	v_sub_f32_e32 v18, v40, v59
	v_exp_f32_e32 v215, v18
	v_sub_f32_e32 v18, v41, v59
	v_exp_f32_e32 v219, v18
	v_sub_f32_e32 v18, v42, v59
	v_exp_f32_e32 v197, v18
	v_sub_f32_e32 v18, v43, v59
	v_exp_f32_e32 v208, v18
	v_sub_f32_e32 v18, v44, v59
	v_exp_f32_e32 v198, v18
	v_sub_f32_e32 v18, v45, v59
	v_exp_f32_e32 v209, v18
	v_sub_f32_e32 v18, v46, v59
	v_exp_f32_e32 v199, v18
	v_sub_f32_e32 v18, v47, v59
	v_exp_f32_e32 v210, v18
	v_sub_f32_e32 v18, v48, v59
	v_exp_f32_e32 v207, v18
	v_sub_f32_e32 v18, v49, v59
	v_exp_f32_e32 v211, v18
	v_lshlrev_b32_e32 v18, 1, v115
	v_add_f32_e32 v162, 0, v59
	v_sub_f32_e32 v99, v19, v59
	v_and_b32_e32 v18, 0xc0, v18
	v_lshlrev_b32_e32 v19, 1, v114
	v_xor_b32_e32 v82, 0x80000000, v162
	v_or3_b32 v54, v18, v19, v54
	v_lshlrev_b32_e32 v18, 1, v53
	v_mov_b32_e32 v83, v82
	v_mov_b32_e32 v84, v82
	v_mov_b32_e32 v85, v82
	v_mov_b32_e32 v86, v82
	v_mov_b32_e32 v87, v82
	v_mov_b32_e32 v88, v82
	v_mov_b32_e32 v89, v82
	v_mov_b32_e32 v90, v82
	v_mov_b32_e32 v91, v82
	v_mov_b32_e32 v92, v82
	v_mov_b32_e32 v93, v82
	v_mov_b32_e32 v94, v82
	v_mov_b32_e32 v95, v82
	v_mov_b32_e32 v96, v82
	v_mov_b32_e32 v97, v82
	v_and_b32_e32 v18, 0xc0, v18
	s_waitcnt vmcnt(4) lgkmcnt(0)
	s_barrier
	v_or3_b32 v60, v18, v19, v60
	v_sub_f32_e32 v113, v33, v59
	v_sub_f32_e32 v112, v32, v59
	v_sub_f32_e32 v111, v31, v59
	v_sub_f32_e32 v110, v30, v59
	v_sub_f32_e32 v109, v29, v59
	v_sub_f32_e32 v108, v28, v59
	v_sub_f32_e32 v107, v27, v59
	v_sub_f32_e32 v106, v26, v59
	v_sub_f32_e32 v105, v25, v59
	v_sub_f32_e32 v104, v24, v59
	v_sub_f32_e32 v103, v23, v59
	v_sub_f32_e32 v102, v22, v59
	v_sub_f32_e32 v101, v21, v59
	v_sub_f32_e32 v100, v20, v59
	v_lshl_add_u64 v[168:169], s[14:15], 0, v[54:55]
	v_lshl_add_u64 v[170:171], s[14:15], 0, v[60:61]
	v_mov_b64_e32 v[64:65], v[14:15]
	v_mov_b64_e32 v[48:49], v[14:15]
	v_mov_b64_e32 v[32:33], v[14:15]
	v_mov_b64_e32 v[72:73], v[6:7]
	v_mov_b64_e32 v[70:71], v[4:5]
	v_mov_b64_e32 v[68:69], v[2:3]
	v_mov_b64_e32 v[66:67], v[0:1]
	v_mov_b64_e32 v[62:63], v[12:13]
	v_mov_b64_e32 v[60:61], v[10:11]
	v_mov_b64_e32 v[58:59], v[8:9]
	v_mov_b64_e32 v[56:57], v[6:7]
	v_mov_b64_e32 v[54:55], v[4:5]
	v_mov_b64_e32 v[52:53], v[2:3]
	v_mov_b64_e32 v[50:51], v[0:1]
	v_mov_b64_e32 v[46:47], v[12:13]
	v_mov_b64_e32 v[44:45], v[10:11]
	v_mov_b64_e32 v[42:43], v[8:9]
	v_mov_b64_e32 v[40:41], v[6:7]
	v_mov_b64_e32 v[38:39], v[4:5]
	v_mov_b64_e32 v[36:37], v[2:3]
	v_mov_b64_e32 v[34:35], v[0:1]
	v_mov_b64_e32 v[30:31], v[12:13]
	v_mov_b64_e32 v[28:29], v[10:11]
	v_mov_b64_e32 v[26:27], v[8:9]
	v_mov_b64_e32 v[24:25], v[6:7]
	v_mov_b64_e32 v[22:23], v[4:5]
	v_mov_b64_e32 v[20:21], v[2:3]
	v_mov_b64_e32 v[18:19], v[0:1]
